# gdn_prep: LDS reads of the diagonal solve, the k_tail image, the block substitution and the output stage hoisted to the top of each stage, waits re-derived
# speedup vs baseline: 1.0028x; 1.0028x over previous
; DI unsigned pk2(float lo, float hi) { f32x2_t v = {lo, hi}; bf16x2_t b = __builtin_convertvector(v, bf16x2_t); return __builtin_bit_cast(unsigned, b); }
; #define MFMA16(a, b, c) __builtin_amdgcn_mfma_f32_16x16x32_bf16((a), (b), (c), 0, 0, 0)
; DI void gdn_prep_unit(const Params& P, int h, int n, unsigned char* lds, int tid, u32x4 (&raw)[12], float& sbv, float& sav, int unext, bool cw_lds = false) {
;     ...
;     { const int l15 = lane & 15, g = lane >> 4;
;       u32x2 xh[4];
; #pragma unroll
;       for (int b = 0; b < 4; ++b) {
;           float* xp = X + (16 * b + 4 * g) * 132 + 16 * wave + l15;
;           f32x4 acc = {xp[0], xp[132], xp[264], xp[396]};
; #pragma unroll
;           for (int bp = 0; bp < b; bp += 2) {
;               const f32x4 a0 = *(const f32x4*)(Ml + (16 * b + l15) * 68 + 16 * bp + 4 * g);
;               f32x4 a1 = {0.f, 0.f, 0.f, 0.f}; u32x2 x1 = {0u, 0u};
;               if (bp + 1 < b) { a1 = *(const f32x4*)(Ml + (16 * b + l15) * 68 + 16 * (bp + 1) + 4 * g); x1 = xh[bp + 1]; }
;               u32x4 ap; ap.x = pk2(-a0[0], -a0[1]); ap.y = pk2(-a0[2], -a0[3]); ap.z = pk2(-a1[0], -a1[1]); ap.w = pk2(-a1[2], -a1[3]);
;               u32x4 bpk; bpk.x = xh[bp].x; bpk.y = xh[bp].y; bpk.z = x1.x; bpk.w = x1.y;
;               acc = MFMA16(__builtin_bit_cast(bf16x8, ap), __builtin_bit_cast(bf16x8, bpk), acc); }
;           const f32x4 tt = *(const f32x4*)(Tl + (16 * b + l15) * 20 + 4 * g);
;           f32x4 xb = {0.f, 0.f, 0.f, 0.f};
;           { u32x4 tp; tp.x = pk2(tt[0], tt[1]); tp.y = pk2(tt[2], tt[3]); tp.z = 0u; tp.w = 0u;
;             u32x4 rp; rp.x = pk2(acc[0], acc[1]); rp.y = pk2(acc[2], acc[3]); rp.z = 0u; rp.w = 0u;
;             xb = MFMA16(__builtin_bit_cast(bf16x8, tp), __builtin_bit_cast(bf16x8, rp), xb); }
;           xh[b].x = pk2(xb[0], xb[1]); xh[b].y = pk2(xb[2], xb[3]);
;           xp[0] = xb[0]; xp[132] = xb[1]; xp[264] = xb[2]; xp[396] = xb[3];
;       } }
.LBB0_491:
	s_or_b64 exec, exec, s[0:1]
	s_waitcnt lgkmcnt(0)
	s_barrier
	v_add_u32_e32 v104, 0x8c00, v215
	ds_read2_b32 v[222:223], v104 offset1:132
	v_add_u32_e32 v105, 0x9000, v215
	ds_read2_b32 v[224:225], v105 offset0:8 offset1:140
	ds_read_b128 v[226:229], v216
	v_add_u32_e32 v106, 0xac00, v215
	ds_read2_b32 v[230:231], v106 offset0:64 offset1:196
	v_add_u32_e32 v107, 0xb000, v215
	ds_read2_b32 v[232:233], v107 offset0:72 offset1:204
	ds_read_b128 v[234:237], v207 offset:18432
	ds_read_b128 v[240:243], v216 offset:1280
	v_add_u32_e32 v62, 0x8c00, v215
	v_add_u32_e32 v63, 0x9000, v215
	v_add_u32_e32 v66, 0xac00, v215
	v_add_u32_e32 v67, 0xb000, v215
	s_mov_b32 s79, s78
	s_waitcnt lgkmcnt(6)
	v_cvt_pk_bf16_f32 v58, v222, v223
	s_waitcnt lgkmcnt(4)
	v_cvt_pk_bf16_f32 v52, v226, v227
	v_cvt_pk_bf16_f32 v53, v228, v229
	v_mov_b32_e32 v54, v42
	v_mov_b32_e32 v55, v42
	v_cvt_pk_bf16_f32 v59, v224, v225
	v_mov_b32_e32 v60, v42
	v_mov_b32_e32 v61, v42
	v_add_u32_e32 v70, 0xce00, v215
	v_add_u32_e32 v71, 0xd200, v215
	v_mfma_f32_16x16x32_bf16 v[58:61], v[52:55], v[58:61], 0
	s_nop 7
	ds_write2_b32 v62, v58, v59 offset1:132
	ds_write2_b32 v63, v60, v61 offset0:8 offset1:140
	v_cvt_pk_bf16_f32 v52, v58, v59
	v_cvt_pk_bf16_f32 v53, v60, v61
	v_add_u32_e32 v72, 0xee00, v215
	v_add_u32_e32 v73, 0xf200, v215
	s_movk_i32 s0, 0x1000
	s_add_u32 s96, s96, 0x8000
	s_waitcnt lgkmcnt(3)
	v_xor_b32_e32 v54, 0x80000000, v235
	v_xor_b32_e32 v55, 0x80000000, v234
	v_cvt_pk_bf16_f32 v54, v55, v54
	v_xor_b32_e32 v55, 0x80000000, v236
	v_xor_b32_e32 v62, 0x80000000, v237
	v_cvt_pk_bf16_f32 v55, v55, v62
	v_mov_b64_e32 v[62:63], s[76:77]
	v_mov_b64_e32 v[64:65], s[78:79]
	v_mov_b32_e32 v62, v54
	v_mov_b32_e32 v63, v55
	v_mov_b32_e32 v54, v42
	v_mov_b32_e32 v55, v42
	s_addc_u32 s97, s97, 0
	s_add_i32 s3, s3, 8
	v_mfma_f32_16x16x32_bf16 v[58:61], v[62:65], v[52:55], v[230:233]
	s_add_u32 s4, s4, 4
	s_addc_u32 s5, s5, 0
	s_cmp_eq_u32 s96, 0x40000
	s_waitcnt lgkmcnt(2)
	v_cvt_pk_bf16_f32 v62, v240, v241
	v_cvt_pk_bf16_f32 v63, v242, v243
	v_mov_b32_e32 v64, v42
	v_mov_b32_e32 v65, v42
	v_cvt_pk_bf16_f32 v58, v58, v59
	v_cvt_pk_bf16_f32 v59, v60, v61
	v_mov_b32_e32 v60, v42
	v_mov_b32_e32 v61, v42
	s_nop 1
	v_mfma_f32_16x16x32_bf16 v[58:61], v[62:65], v[58:61], 0
	s_nop 7
	ds_write2_b32 v66, v58, v59 offset0:64 offset1:196
	ds_write2_b32 v67, v60, v61 offset0:72 offset1:204
	v_cvt_pk_bf16_f32 v54, v58, v59
	v_cvt_pk_bf16_f32 v55, v60, v61
	ds_read2_b32 v[222:223], v70 offset1:132
	ds_read2_b32 v[224:225], v71 offset0:8 offset1:140
	ds_read_b128 v[226:229], v208 offset:18432
	ds_read_b128 v[230:233], v208 offset:18496
	ds_read_b128 v[234:237], v216 offset:2560
	ds_read2_b32 v[240:241], v72 offset0:64 offset1:196
	ds_read2_b32 v[242:243], v73 offset0:72 offset1:204
	ds_read_b128 v[244:247], v209 offset:18432
	ds_read_b128 v[248:251], v209 offset:18496
	ds_read_b128 v[252:255], v209 offset:18560
	ds_read_b128 v[100:103], v216 offset:3840
	s_waitcnt lgkmcnt(8)
	v_xor_b32_e32 v63, 0x80000000, v227
	v_xor_b32_e32 v62, 0x80000000, v226
	v_cvt_pk_bf16_f32 v62, v62, v63
	v_xor_b32_e32 v63, 0x80000000, v228
	v_xor_b32_e32 v64, 0x80000000, v229
	v_cvt_pk_bf16_f32 v63, v63, v64
	s_waitcnt lgkmcnt(7)
	v_xor_b32_e32 v64, 0x80000000, v231
	v_xor_b32_e32 v65, 0x80000000, v230
	v_cvt_pk_bf16_f32 v64, v65, v64
	v_xor_b32_e32 v65, 0x80000000, v232
	v_xor_b32_e32 v66, 0x80000000, v233
	v_cvt_pk_bf16_f32 v65, v65, v66
	s_nop 1
	v_mfma_f32_16x16x32_bf16 v[58:61], v[62:65], v[52:55], v[222:225]
	s_waitcnt lgkmcnt(6)
	v_cvt_pk_bf16_f32 v62, v234, v235
	v_cvt_pk_bf16_f32 v63, v236, v237
	v_mov_b32_e32 v64, v42
	v_mov_b32_e32 v65, v42
	s_nop 1
	s_nop 0
	v_cvt_pk_bf16_f32 v58, v58, v59
	v_cvt_pk_bf16_f32 v59, v60, v61
	v_mov_b32_e32 v60, v42
	v_mov_b32_e32 v61, v42
	s_nop 1
	v_mfma_f32_16x16x32_bf16 v[58:61], v[62:65], v[58:61], 0
	s_nop 7
	ds_write2_b32 v70, v58, v59 offset1:132
	ds_write2_b32 v71, v60, v61 offset0:8 offset1:140
	v_cvt_pk_bf16_f32 v62, v58, v59
	v_cvt_pk_bf16_f32 v63, v60, v61
	s_waitcnt lgkmcnt(5)
	v_xor_b32_e32 v65, 0x80000000, v245
	v_xor_b32_e32 v64, 0x80000000, v244
	v_cvt_pk_bf16_f32 v64, v64, v65
	v_xor_b32_e32 v65, 0x80000000, v246
	v_xor_b32_e32 v66, 0x80000000, v247
	v_cvt_pk_bf16_f32 v65, v65, v66
	s_waitcnt lgkmcnt(4)
	v_xor_b32_e32 v66, 0x80000000, v249
	v_xor_b32_e32 v67, 0x80000000, v248
	v_cvt_pk_bf16_f32 v66, v67, v66
	v_xor_b32_e32 v67, 0x80000000, v250
	v_xor_b32_e32 v68, 0x80000000, v251
	v_cvt_pk_bf16_f32 v67, v67, v68
	s_nop 1
	v_mfma_f32_16x16x32_bf16 v[52:55], v[64:67], v[52:55], v[240:243]
	s_nop 2
	s_waitcnt lgkmcnt(3)
	v_xor_b32_e32 v59, 0x80000000, v253
	v_xor_b32_e32 v58, 0x80000000, v252
	v_cvt_pk_bf16_f32 v64, v58, v59
	v_xor_b32_e32 v58, 0x80000000, v254
	v_xor_b32_e32 v59, 0x80000000, v255
	v_cvt_pk_bf16_f32 v65, v58, v59
	v_mov_b64_e32 v[58:59], s[76:77]
	v_mov_b64_e32 v[60:61], s[78:79]
	v_mov_b32_e32 v58, v64
	v_mov_b32_e32 v59, v65
	v_mov_b32_e32 v64, v42
	v_mov_b32_e32 v65, v42
	s_nop 1
	v_mfma_f32_16x16x32_bf16 v[52:55], v[58:61], v[62:65], v[52:55]
	s_waitcnt lgkmcnt(2)
	v_cvt_pk_bf16_f32 v58, v100, v101
	v_cvt_pk_bf16_f32 v59, v102, v103
	v_mov_b32_e32 v60, v42
	v_mov_b32_e32 v61, v42
	s_nop 1
	s_nop 0
	v_cvt_pk_bf16_f32 v52, v52, v53
	v_cvt_pk_bf16_f32 v53, v54, v55
	v_mov_b32_e32 v54, v42
	v_mov_b32_e32 v55, v42
	s_nop 1
	v_mfma_f32_16x16x32_bf16 v[52:55], v[58:61], v[52:55], 0
	s_nop 7
	ds_write2_b32 v72, v52, v53 offset0:64 offset1:196
	ds_write2_b32 v73, v54, v55 offset0:72 offset1:204
	s_waitcnt lgkmcnt(0)
	s_barrier
; DI unsigned pk2(float lo, float hi) { f32x2_t v = {lo, hi}; bf16x2_t b = __builtin_convertvector(v, bf16x2_t); return __builtin_bit_cast(unsigned, b); }
; DI void gdn_prep_unit(const Params& P, int h, int n, unsigned char* lds, int tid, u32x4 (&raw)[12], float& sbv, float& sav, int unext, bool cw_lds = false) {
;     ...
;     { bf16_t* WB = (bf16_t*)(ws + WS_WB) + (size_t)unit * 4096;
; #pragma unroll
;       for (int k = 0; k < 2; ++k) { const int gidx = tid + 512 * k, cgi = gidx >> 8, mb = (gidx >> 6) & 3, l = gidx & 63;
;           const float* xp = X + (16 * mb + 4 * (l >> 4)) * 132 + 16 * cgi + (l & 15);
;           u32x2 o; o.x = pk2(xp[0], xp[132]); o.y = pk2(xp[264], xp[396]); *(u32x2*)(WB + gidx * 4) = o; }
;       const int c = tid >> 3, pg = tid & 7, s = pg >> 2, g = pg & 3;
;       float v[8];
; #pragma unroll
;       for (int j = 0; j < 8; ++j) { const int d = 32 * s + 16 * (j >> 2) + 4 * g + (j & 3); v[j] = -X[c * 132 + 64 + d]; }
;       u32x4 o1; o1.x = pk2(v[0], v[1]); o1.y = pk2(v[2], v[3]); o1.z = pk2(v[4], v[5]); o1.w = pk2(v[6], v[7]);
;       *(u32x4*)(IMG + c * 64 + 8 * ((pg ^ (c >> 1)) & 7)) = o1; }
	v_add_u32_e32 v104, 0x8c00, v210
	ds_read2_b32 v[222:223], v104 offset1:132
	v_add_u32_e32 v105, 0x8d40, v212
	ds_read2_b32 v[224:225], v105 offset1:1
	v_add_u32_e32 v106, 0x8d48, v212
	ds_read2_b32 v[226:227], v106 offset1:1
	v_add_u32_e32 v107, 0x9000, v210
	ds_read2_b32 v[228:229], v107 offset0:8 offset1:140
	v_add_u32_e32 v108, 0x8c00, v211
	ds_read2_b32 v[230:231], v108 offset1:132
	v_add_u32_e32 v109, 0x9000, v211
	ds_read2_b32 v[232:233], v109 offset0:8 offset1:140
	ds_read_b128 v[234:237], v212 offset:36096
	v_add_u32_e32 v52, 0x8c00, v210
	v_add_u32_e32 v58, 0x8d40, v212
	v_add_u32_e32 v60, 0x8d48, v212
	s_waitcnt lgkmcnt(6)
	v_cvt_pk_bf16_f32 v52, v222, v223
	v_add_u32_e32 v53, 0x9000, v210
	s_waitcnt lgkmcnt(3)
	v_cvt_pk_bf16_f32 v53, v228, v229
	global_store_dwordx2 v[86:87], v[52:53], off
	v_add_u32_e32 v52, 0x8c00, v211
	s_waitcnt lgkmcnt(2)
	v_cvt_pk_bf16_f32 v52, v230, v231
	v_add_u32_e32 v53, 0x9000, v211
	s_waitcnt lgkmcnt(1)
	v_cvt_pk_bf16_f32 v53, v232, v233
	v_add_co_u32_e32 v54, vcc, s0, v86
	s_nop 1
	v_addc_co_u32_e32 v55, vcc, 0, v87, vcc
	global_store_dwordx2 v[54:55], v[52:53], off
	v_lshl_add_u64 v[86:87], v[86:87], 0, s[84:85]
	s_waitcnt lgkmcnt(0)
	v_pk_add_f32 v[52:53], v[234:235], 0 neg_lo:[1,1] neg_hi:[1,1]
	v_pk_add_f32 v[54:55], v[236:237], 0 neg_lo:[1,1] neg_hi:[1,1]
	v_cvt_pk_bf16_f32 v52, v52, v53
	v_cvt_pk_bf16_f32 v53, v54, v55
	v_pk_add_f32 v[54:55], v[224:225], 0 neg_lo:[1,1] neg_hi:[1,1]
	v_pk_add_f32 v[58:59], v[226:227], 0 neg_lo:[1,1] neg_hi:[1,1]
	v_cvt_pk_bf16_f32 v54, v54, v55
	v_cvt_pk_bf16_f32 v55, v58, v59
	global_store_dwordx4 v[56:57], v[52:55], off
	v_mov_b32_e32 v60, v226
	v_mov_b32_e32 v61, v227
	s_cbranch_scc1 .LBB0_576

; DI float bf2f(bf16_t v) { return __uint_as_float(((unsigned)v) << 16); }
; DI unsigned pk2(float lo, float hi) { f32x2_t v = {lo, hi}; bf16x2_t b = __builtin_convertvector(v, bf16x2_t); return __builtin_bit_cast(unsigned, b); }
; DI void gdn_prep_unit(const Params& P, int h, int n, unsigned char* lds, int tid, u32x4 (&raw)[12], float& sbv, float& sav, int unext, bool cw_lds = false) {
;     ...
;     else {
;       const float glast = gcs[63];
; #pragma unroll
;       for (int k2 = 0; k2 < 2; ++k2) { const int it_ = (tid - 256) + 256 * k2, c = it_ >> 3, pg = it_ & 7, s = pg >> 2, g = pg & 3;
;           float w[8];
; #pragma unroll
;           for (int j = 0; j < 8; ++j) { const int d = 32 * s + 16 * (j >> 2) + 4 * g + (j & 3); w[j] = bf2f(Kimg[d * 72 + c]) * __expf(glast - gcs[d]); }
;           u32x4 o2; o2.x = pk2(w[0], w[1]); o2.y = pk2(w[2], w[3]); o2.z = pk2(w[4], w[5]); o2.w = pk2(w[6], w[7]);
;           *(u32x4*)(IMG + 12288 + c * 64 + 8 * ((pg ^ (c >> 1)) & 7)) = o2;
;           *(u32x4*)(IMG + 8192 + it_ * 8) = *(const u32x4*)(Aimg + it_ * 8); }
;       if (tid == 256) ((float*)(ws + WS_GL))[unit] = __expf(glast); }
.LBB0_570:
	v_lshl_add_u64 v[56:57], v[94:95], 0, s[96:97]
	s_and_saveexec_b64 s[0:1], s[88:89]
	s_xor_b64 s[0:1], exec, s[0:1]
	s_cbranch_execz .LBB0_574
	v_mov_b32_e32 v118, s59
	ds_read_b32 v222, v118
	ds_read_b128 v[224:227], v157
	ds_read_u16 v228, v130
	ds_read_u16 v229, v130 offset:144
	ds_read_u16 v230, v130 offset:288
	ds_read_u16 v231, v130 offset:432
	ds_read_b128 v[232:235], v158
	ds_read_u16 v236, v130 offset:2304
	ds_read_u16 v237, v130 offset:2448
	ds_read_u16 v240, v130 offset:2592
	ds_read_u16 v241, v130 offset:2736
	ds_read_b128 v[242:245], v159
	ds_read_u16 v246, v131
	ds_read_u16 v247, v131 offset:144
	ds_read_u16 v248, v131 offset:288
	ds_read_u16 v249, v131 offset:432
	ds_read_u16 v250, v131 offset:2304
	ds_read_u16 v251, v131 offset:2448
	ds_read_u16 v252, v131 offset:2592
	ds_read_u16 v253, v131 offset:2736
	ds_read_b128 v[100:103], v160
	v_mov_b32_e32 v52, s59
	s_waitcnt lgkmcnt(15)
	v_sub_f32_e32 v52, v222, v224
	v_mul_f32_e32 v52, 0x3fb8aa3b, v52
	v_exp_f32_e32 v54, v52
	v_sub_f32_e32 v52, v222, v225
	v_mul_f32_e32 v52, 0x3fb8aa3b, v52
	v_exp_f32_e32 v55, v52
	s_waitcnt lgkmcnt(15)
	v_lshlrev_b32_e32 v52, 16, v228
	s_waitcnt lgkmcnt(15)
	v_lshlrev_b32_e32 v53, 16, v229
	v_pk_mul_f32 v[58:59], v[54:55], v[52:53]
	v_sub_f32_e32 v52, v222, v226
	v_sub_f32_e32 v53, v222, v227
	v_mul_f32_e32 v52, 0x3fb8aa3b, v52
	v_mul_f32_e32 v53, 0x3fb8aa3b, v53
	v_exp_f32_e32 v52, v52
	v_exp_f32_e32 v53, v53
	s_waitcnt lgkmcnt(15)
	v_lshlrev_b32_e32 v61, 16, v231
	v_lshlrev_b32_e32 v60, 16, v230
	v_pk_mul_f32 v[62:63], v[52:53], v[60:61]
	s_waitcnt lgkmcnt(14)
	v_sub_f32_e32 v60, v222, v232
	v_sub_f32_e32 v61, v222, v233
	v_mul_f32_e32 v60, 0x3fb8aa3b, v60
	v_mul_f32_e32 v61, 0x3fb8aa3b, v61
	v_exp_f32_e32 v60, v60
	v_exp_f32_e32 v61, v61
	s_waitcnt lgkmcnt(12)
	v_lshlrev_b32_e32 v65, 16, v237
	v_lshlrev_b32_e32 v64, 16, v236
	v_pk_mul_f32 v[72:73], v[60:61], v[64:65]
	v_sub_f32_e32 v64, v222, v234
	v_sub_f32_e32 v65, v222, v235
	v_mul_f32_e32 v64, 0x3fb8aa3b, v64
	v_mul_f32_e32 v65, 0x3fb8aa3b, v65
	v_exp_f32_e32 v64, v64
	v_exp_f32_e32 v65, v65
	s_waitcnt lgkmcnt(10)
	v_lshlrev_b32_e32 v69, 16, v241
	v_lshlrev_b32_e32 v68, 16, v240
	v_cvt_pk_bf16_f32 v70, v72, v73
	v_pk_mul_f32 v[74:75], v[64:65], v[68:69]
	v_cvt_pk_bf16_f32 v68, v58, v59
	v_cvt_pk_bf16_f32 v69, v62, v63
	v_cvt_pk_bf16_f32 v71, v74, v75
	v_lshl_add_u64 v[58:59], v[92:93], 0, s[96:97]
	global_store_dwordx4 v[58:59], v[68:71], off
	v_lshl_add_u64 v[58:59], v[96:97], 0, s[96:97]
	s_waitcnt lgkmcnt(9)
	global_store_dwordx4 v[58:59], v[242:245], off
	s_waitcnt lgkmcnt(8)
	v_lshlrev_b32_e32 v58, 16, v246
	s_waitcnt lgkmcnt(7)
	v_lshlrev_b32_e32 v59, 16, v247
	v_pk_mul_f32 v[54:55], v[54:55], v[58:59]
	s_waitcnt lgkmcnt(6)
	v_lshlrev_b32_e32 v58, 16, v248
	s_waitcnt lgkmcnt(5)
	v_lshlrev_b32_e32 v59, 16, v249
	v_pk_mul_f32 v[58:59], v[52:53], v[58:59]
	s_waitcnt lgkmcnt(4)
	v_lshlrev_b32_e32 v52, 16, v250
	s_waitcnt lgkmcnt(3)
	v_lshlrev_b32_e32 v53, 16, v251
	v_pk_mul_f32 v[60:61], v[60:61], v[52:53]
	s_waitcnt lgkmcnt(2)
	v_lshlrev_b32_e32 v52, 16, v252
	s_waitcnt lgkmcnt(1)
	v_lshlrev_b32_e32 v53, 16, v253
	v_pk_mul_f32 v[62:63], v[64:65], v[52:53]
	v_cvt_pk_bf16_f32 v53, v58, v59
	v_add_co_u32_e32 v58, vcc, 0x6000, v56
	v_cvt_pk_bf16_f32 v52, v54, v55
	v_cvt_pk_bf16_f32 v54, v60, v61
	v_cvt_pk_bf16_f32 v55, v62, v63
	v_addc_co_u32_e32 v59, vcc, 0, v57, vcc
	global_store_dwordx4 v[58:59], v[52:55], off
	v_lshl_add_u64 v[58:59], v[98:99], 0, s[96:97]
	s_waitcnt lgkmcnt(0)
	global_store_dwordx4 v[58:59], v[100:103], off
	v_mov_b32_e32 v52, v100
	v_mov_b32_e32 v53, v101
	v_mov_b32_e32 v54, v102
	v_mov_b32_e32 v55, v103
	v_mov_b32_e32 v66, v222
	v_mov_b32_e32 v67, v240
	v_mov_b32_e32 v68, v242
	v_mov_b32_e32 v69, v243
	v_mov_b32_e32 v70, v244
	v_mov_b32_e32 v71, v245
	s_and_saveexec_b64 s[54:55], s[44:45]
	s_cbranch_execz .LBB0_573
	v_mul_f32_e32 v52, 0x3fb8aa3b, v66
	v_exp_f32_e32 v52, v52
	global_store_dword v42, v52, s[4:5]

; DI float dpp_xor1(float v) { return __int_as_float(__builtin_amdgcn_update_dpp(0, __float_as_int(v), 0xB1, 0xf, 0xf, false)); }
; DI float dpp_xor2(float v) { return __int_as_float(__builtin_amdgcn_update_dpp(0, __float_as_int(v), 0x4E, 0xf, 0xf, false)); }
; DI void gdn_prep_unit(const Params& P, int h, int n, unsigned char* lds, int tid, u32x4 (&raw)[12], float& sbv, float& sav, int unext, bool cw_lds = false) {
;     ...
;     if (wave < 4) { const int b = wave, col = lane >> 2, q4 = lane & 3;
;       float xr[4] = {0.f, 0.f, 0.f, 0.f};
; #pragma unroll
;       for (int p = 0; p < 8; ++p) { const int i0 = 2 * p, i1 = 2 * p + 1;
;           const float* d0 = Ml + (16 * b + i0) * 68 + 16 * b; const float* d1 = Ml + (16 * b + i1) * 68 + 16 * b;
;           float p0 = 0.f, p1 = 0.f;
; #pragma unroll
;           for (int m = 0; m < (i1 + 3) / 4; ++m) { p0 += d0[4 * m + q4] * xr[m]; p1 += d1[4 * m + q4] * xr[m]; }
;           p0 += dpp_xor1(p0); p1 += dpp_xor1(p1); p0 += dpp_xor2(p0); p1 += dpp_xor2(p1);
;           const float x0 = (i0 == col ? 1.f : 0.f) - p0;
;           const float x1 = (i1 == col ? 1.f : 0.f) - p1 - d1[i0] * x0;
;           if (q4 == (i0 & 3)) xr[i0 >> 2] = x0;
;           if (q4 == (i1 & 3)) xr[i1 >> 2] = x1;
;           Tl[(16 * b + i0) * 20 + col] = x0; Tl[(16 * b + i1) * 20 + col] = x1;
;       } }
.LBB0_574:
	s_andn2_saveexec_b64 s[0:1], s[0:1]
	s_cbranch_execz .LBB0_491
	ds_read_b32 v222, v168 offset:18432
	ds_read_b32 v223, v169 offset:18432
	ds_read_b32 v224, v161 offset:18432
	ds_read_b32 v225, v174 offset:18432
	ds_read_b32 v226, v173 offset:18432
	ds_read_b32 v227, v172 offset:18440
	ds_read2_b32 v[228:229], v220 offset1:4
	v_add_u32_e32 v66, 0x4800, v178
	ds_read2_b32 v[230:231], v66 offset1:4
	ds_read_b32 v232, v177 offset:18448
	ds_read2_b32 v[234:235], v221 offset1:4
	v_add_u32_e32 v67, 0x4800, v182
	ds_read2_b32 v[236:237], v67 offset1:4
	ds_read_b32 v240, v181 offset:18456
	v_add_u32_e32 v68, 0x4800, v187
	ds_read2_b32 v[242:243], v68 offset1:4
	ds_read_b32 v244, v187 offset:18464
	v_add_u32_e32 v69, 0x4800, v188
	ds_read2_b32 v[246:247], v69 offset1:4
	ds_read_b32 v248, v188 offset:18464
	ds_read_b32 v249, v186 offset:18464
	v_add_u32_e32 v70, 0x4800, v192
	ds_read2_b32 v[250:251], v70 offset1:4
	ds_read_b32 v252, v192 offset:18464
	v_add_u32_e32 v71, 0x4800, v193
	ds_read2_b32 v[254:255], v71 offset1:4
	ds_read_b32 v100, v193 offset:18464
	ds_read_b32 v101, v191 offset:18472
	v_add_u32_e32 v72, 0x4800, v198
	ds_read2_b32 v[102:103], v72 offset1:4
	ds_read2_b32 v[104:105], v72 offset0:8 offset1:12
	v_add_u32_e32 v73, 0x4800, v199
	ds_read2_b32 v[106:107], v73 offset1:4
	ds_read2_b32 v[108:109], v73 offset0:8 offset1:12
	ds_read_b32 v110, v197 offset:18480
	v_add_u32_e32 v74, 0x4800, v203
	ds_read2_b32 v[112:113], v74 offset1:4
	ds_read2_b32 v[114:115], v74 offset0:8 offset1:12
	v_add_u32_e32 v75, 0x4800, v204
	ds_read2_b32 v[118:119], v75 offset1:4
	ds_read2_b32 v[120:121], v75 offset0:8 offset1:12
	ds_read_b32 v80, v202 offset:18488
	s_waitcnt lgkmcnt(15)
	v_fma_f32 v52, v222, 0, 0
	s_waitcnt lgkmcnt(15)
	v_fma_f32 v53, v223, 0, 0
	v_add_f32_dpp v52, v52, v52 quad_perm:[1,0,3,2] row_mask:0xf bank_mask:0xf bound_ctrl:1
	s_nop 0
	v_add_f32_dpp v53, v53, v53 quad_perm:[1,0,3,2] row_mask:0xf bank_mask:0xf bound_ctrl:1
	v_add_f32_dpp v52, v52, v52 quad_perm:[2,3,0,1] row_mask:0xf bank_mask:0xf bound_ctrl:1
	v_sub_f32_e32 v52, v170, v52
	v_add_f32_dpp v53, v53, v53 quad_perm:[2,3,0,1] row_mask:0xf bank_mask:0xf bound_ctrl:1
	v_sub_f32_e32 v53, v171, v53
	s_waitcnt lgkmcnt(15)
	v_fma_f32 v53, -v224, v52, v53
	v_cndmask_b32_e64 v54, 0, v52, s[46:47]
	ds_write_b32 v213, v52
	ds_write_b32 v214, v53
	v_cndmask_b32_e64 v54, v54, v53, s[48:49]
	s_waitcnt lgkmcnt(15)
	v_fma_f32 v52, v225, v54, 0
	s_waitcnt lgkmcnt(15)
	v_fma_f32 v53, v54, v226, 0
	v_add_f32_dpp v52, v52, v52 quad_perm:[1,0,3,2] row_mask:0xf bank_mask:0xf bound_ctrl:1
	s_nop 0
	v_add_f32_dpp v53, v53, v53 quad_perm:[1,0,3,2] row_mask:0xf bank_mask:0xf bound_ctrl:1
	v_add_f32_dpp v52, v52, v52 quad_perm:[2,3,0,1] row_mask:0xf bank_mask:0xf bound_ctrl:1
	v_sub_f32_e32 v52, v175, v52
	v_add_f32_dpp v53, v53, v53 quad_perm:[2,3,0,1] row_mask:0xf bank_mask:0xf bound_ctrl:1
	v_sub_f32_e32 v53, v176, v53
	s_waitcnt lgkmcnt(15)
	v_fma_f32 v53, -v227, v52, v53
	v_cndmask_b32_e64 v54, v54, v52, s[50:51]
	ds_write2_b32 v214, v52, v53 offset0:20 offset1:40
	v_cndmask_b32_e64 v60, v54, v53, s[52:53]
	v_add_u32_e32 v52, 0x4800, v178
	s_waitcnt lgkmcnt(15)
	v_fma_f32 v54, v228, v60, 0
	s_waitcnt lgkmcnt(15)
	v_fma_f32 v52, v230, v60, 0
	v_fmac_f32_e32 v54, 0, v229
	v_fmac_f32_e32 v52, 0, v231
	s_nop 0
	v_add_f32_dpp v53, v54, v54 quad_perm:[1,0,3,2] row_mask:0xf bank_mask:0xf bound_ctrl:1
	v_add_f32_dpp v52, v52, v52 quad_perm:[1,0,3,2] row_mask:0xf bank_mask:0xf bound_ctrl:1
	s_nop 0
	v_add_f32_dpp v53, v53, v53 quad_perm:[2,3,0,1] row_mask:0xf bank_mask:0xf bound_ctrl:1
	v_sub_f32_e32 v53, v179, v53
	v_add_f32_dpp v52, v52, v52 quad_perm:[2,3,0,1] row_mask:0xf bank_mask:0xf bound_ctrl:1
	v_sub_f32_e32 v52, v180, v52
	s_waitcnt lgkmcnt(15)
	v_fma_f32 v52, -v232, v53, v52
	v_cndmask_b32_e64 v54, 0, v53, s[46:47]
	ds_write2_b32 v214, v53, v52 offset0:60 offset1:80
	v_cndmask_b32_e64 v58, v54, v52, s[48:49]
	v_add_u32_e32 v52, 0x4800, v182
	s_waitcnt lgkmcnt(15)
	v_fma_f32 v54, v60, v234, 0
	s_waitcnt lgkmcnt(15)
	v_fma_f32 v52, v60, v236, 0
	v_fmac_f32_e32 v54, v58, v235
	v_fmac_f32_e32 v52, v58, v237
	s_nop 0
	v_add_f32_dpp v53, v54, v54 quad_perm:[1,0,3,2] row_mask:0xf bank_mask:0xf bound_ctrl:1
	v_add_f32_dpp v52, v52, v52 quad_perm:[1,0,3,2] row_mask:0xf bank_mask:0xf bound_ctrl:1
	s_nop 0
	v_add_f32_dpp v53, v53, v53 quad_perm:[2,3,0,1] row_mask:0xf bank_mask:0xf bound_ctrl:1
	v_sub_f32_e32 v53, v183, v53
	v_add_f32_dpp v52, v52, v52 quad_perm:[2,3,0,1] row_mask:0xf bank_mask:0xf bound_ctrl:1
	v_sub_f32_e32 v52, v185, v52
	s_waitcnt lgkmcnt(15)
; DI float dpp_xor1(float v) { return __int_as_float(__builtin_amdgcn_update_dpp(0, __float_as_int(v), 0xB1, 0xf, 0xf, false)); }
; DI float dpp_xor2(float v) { return __int_as_float(__builtin_amdgcn_update_dpp(0, __float_as_int(v), 0x4E, 0xf, 0xf, false)); }
; DI void gdn_prep_unit(const Params& P, int h, int n, unsigned char* lds, int tid, u32x4 (&raw)[12], float& sbv, float& sav, int unext, bool cw_lds = false) {
;     ...
;     if (wave < 4) { const int b = wave, col = lane >> 2, q4 = lane & 3;
;       float xr[4] = {0.f, 0.f, 0.f, 0.f};
; #pragma unroll
;       for (int p = 0; p < 8; ++p) { const int i0 = 2 * p, i1 = 2 * p + 1;
;           const float* d0 = Ml + (16 * b + i0) * 68 + 16 * b; const float* d1 = Ml + (16 * b + i1) * 68 + 16 * b;
;           float p0 = 0.f, p1 = 0.f;
; #pragma unroll
;           for (int m = 0; m < (i1 + 3) / 4; ++m) { p0 += d0[4 * m + q4] * xr[m]; p1 += d1[4 * m + q4] * xr[m]; }
;           p0 += dpp_xor1(p0); p1 += dpp_xor1(p1); p0 += dpp_xor2(p0); p1 += dpp_xor2(p1);
;           const float x0 = (i0 == col ? 1.f : 0.f) - p0;
;           const float x1 = (i1 == col ? 1.f : 0.f) - p1 - d1[i0] * x0;
;           if (q4 == (i0 & 3)) xr[i0 >> 2] = x0;
;           if (q4 == (i1 & 3)) xr[i1 >> 2] = x1;
;           Tl[(16 * b + i0) * 20 + col] = x0; Tl[(16 * b + i1) * 20 + col] = x1;
;       } }
	v_fma_f32 v52, -v240, v53, v52
	v_cndmask_b32_e64 v54, v58, v53, s[50:51]
	v_cndmask_b32_e64 v61, v54, v52, s[52:53]
	ds_write2_b32 v214, v53, v52 offset0:100 offset1:120
	v_add_u32_e32 v52, 0x4800, v187
	s_waitcnt lgkmcnt(15)
	v_fma_f32 v55, v60, v242, 0
	v_add_u32_e32 v52, 0x4800, v188
	v_fmac_f32_e32 v55, v61, v243
	s_waitcnt lgkmcnt(15)
	v_fmac_f32_e32 v55, 0, v244
	s_waitcnt lgkmcnt(15)
	v_fma_f32 v52, v60, v246, 0
	v_fmac_f32_e32 v52, v61, v247
	s_waitcnt lgkmcnt(15)
	v_fmac_f32_e32 v52, 0, v248
	v_add_f32_dpp v53, v55, v55 quad_perm:[1,0,3,2] row_mask:0xf bank_mask:0xf bound_ctrl:1
	s_nop 0
	v_add_f32_dpp v52, v52, v52 quad_perm:[1,0,3,2] row_mask:0xf bank_mask:0xf bound_ctrl:1
	v_add_f32_dpp v53, v53, v53 quad_perm:[2,3,0,1] row_mask:0xf bank_mask:0xf bound_ctrl:1
	v_sub_f32_e32 v53, v190, v53
	v_add_f32_dpp v52, v52, v52 quad_perm:[2,3,0,1] row_mask:0xf bank_mask:0xf bound_ctrl:1
	v_sub_f32_e32 v52, v189, v52
	s_waitcnt lgkmcnt(15)
	v_fma_f32 v53, -v249, v52, v53
	v_cndmask_b32_e64 v54, 0, v52, s[46:47]
	ds_write2_b32 v214, v52, v53 offset0:140 offset1:160
	v_add_u32_e32 v52, 0x4800, v192
	v_cndmask_b32_e64 v54, v54, v53, s[48:49]
	s_waitcnt lgkmcnt(15)
	v_fma_f32 v58, v60, v250, 0
	v_add_u32_e32 v52, 0x4800, v193
	v_fmac_f32_e32 v58, v61, v251
	s_waitcnt lgkmcnt(15)
	v_fmac_f32_e32 v58, v54, v252
	s_waitcnt lgkmcnt(15)
	v_fma_f32 v52, v60, v254, 0
	v_fmac_f32_e32 v52, v61, v255
	s_waitcnt lgkmcnt(15)
	v_fmac_f32_e32 v52, v54, v100
	v_add_f32_dpp v53, v58, v58 quad_perm:[1,0,3,2] row_mask:0xf bank_mask:0xf bound_ctrl:1
	s_nop 0
	v_add_f32_dpp v52, v52, v52 quad_perm:[1,0,3,2] row_mask:0xf bank_mask:0xf bound_ctrl:1
	v_add_f32_dpp v53, v53, v53 quad_perm:[2,3,0,1] row_mask:0xf bank_mask:0xf bound_ctrl:1
	v_sub_f32_e32 v53, v195, v53
	v_add_f32_dpp v52, v52, v52 quad_perm:[2,3,0,1] row_mask:0xf bank_mask:0xf bound_ctrl:1
	v_sub_f32_e32 v52, v194, v52
	s_waitcnt lgkmcnt(15)
	v_fma_f32 v53, -v101, v52, v53
	v_cndmask_b32_e64 v54, v54, v52, s[50:51]
	v_cndmask_b32_e64 v62, v54, v53, s[52:53]
	ds_write2_b32 v214, v52, v53 offset0:180 offset1:200
	v_add_u32_e32 v54, 0x4800, v198
	s_waitcnt lgkmcnt(15)
	v_fma_f32 v63, v60, v102, 0
	v_fmac_f32_e32 v63, v61, v103
	s_waitcnt lgkmcnt(15)
	v_fmac_f32_e32 v63, v62, v104
	v_add_u32_e32 v54, 0x4800, v199
	v_fmac_f32_e32 v63, 0, v105
	s_waitcnt lgkmcnt(14)
	v_fma_f32 v52, v60, v106, 0
	v_fmac_f32_e32 v52, v61, v107
	s_waitcnt lgkmcnt(13)
	v_fmac_f32_e32 v52, v62, v108
	v_fmac_f32_e32 v52, 0, v109
	v_add_f32_dpp v53, v63, v63 quad_perm:[1,0,3,2] row_mask:0xf bank_mask:0xf bound_ctrl:1
	s_nop 0
	v_add_f32_dpp v52, v52, v52 quad_perm:[1,0,3,2] row_mask:0xf bank_mask:0xf bound_ctrl:1
	v_add_f32_dpp v53, v53, v53 quad_perm:[2,3,0,1] row_mask:0xf bank_mask:0xf bound_ctrl:1
	v_sub_f32_e32 v53, v201, v53
	v_add_f32_dpp v52, v52, v52 quad_perm:[2,3,0,1] row_mask:0xf bank_mask:0xf bound_ctrl:1
	v_sub_f32_e32 v52, v200, v52
	s_waitcnt lgkmcnt(12)
	v_fma_f32 v53, -v110, v52, v53
	v_cndmask_b32_e64 v54, 0, v52, s[46:47]
	v_cndmask_b32_e64 v63, v54, v53, s[48:49]
	ds_write2_b32 v214, v52, v53 offset0:220 offset1:240
	v_add_u32_e32 v54, 0x4800, v203
	s_waitcnt lgkmcnt(12)
	v_fma_f32 v64, v60, v112, 0
	v_fmac_f32_e32 v64, v61, v113
	s_waitcnt lgkmcnt(11)
	v_fmac_f32_e32 v64, v62, v114
	v_add_u32_e32 v54, 0x4800, v204
	v_fmac_f32_e32 v64, v63, v115
	s_waitcnt lgkmcnt(10)
	v_fma_f32 v52, v60, v118, 0
	v_fmac_f32_e32 v52, v61, v119
	s_waitcnt lgkmcnt(9)
	v_fmac_f32_e32 v52, v62, v120
	v_fmac_f32_e32 v52, v63, v121
	v_add_f32_dpp v53, v64, v64 quad_perm:[1,0,3,2] row_mask:0xf bank_mask:0xf bound_ctrl:1
	s_nop 0
	v_add_f32_dpp v52, v52, v52 quad_perm:[1,0,3,2] row_mask:0xf bank_mask:0xf bound_ctrl:1
	v_add_f32_dpp v53, v53, v53 quad_perm:[2,3,0,1] row_mask:0xf bank_mask:0xf bound_ctrl:1
	v_sub_f32_e32 v53, v206, v53
	v_add_f32_dpp v52, v52, v52 quad_perm:[2,3,0,1] row_mask:0xf bank_mask:0xf bound_ctrl:1
	v_sub_f32_e32 v52, v205, v52
	s_waitcnt lgkmcnt(8)
	v_fma_f32 v53, -v80, v52, v53
	v_add_u32_e32 v54, 0x400, v214
	ds_write2_b32 v54, v52, v53 offset0:4 offset1:24
	v_mov_b32_e32 v55, v115
	v_mov_b32_e32 v58, v120
	v_mov_b32_e32 v59, v121
	s_branch .LBB0_491
